# static s_setprio 1 for waves 4-7 in the SSD y-loop/state-update segment (wave-pair stagger)
# baseline (speedup 1.0000x reference)
; __device__ __forceinline__ void phase_ssd(KP P, char* smem, const int wv) {
;     ...
;       {
;         const int it = w >> 1, jt0 = (w & 1) * 2;
;         f32x4 cb[2] = {{0.f, 0.f, 0.f, 0.f}, {0.f, 0.f, 0.f, 0.f}};
; #pragma unroll
;         for (int ks = 0; ks < 4; ++ks) {
;           bf16x8 a = lds_b128(sC + (it * 16 + frc) * S_LDB + ks * 32 + fqc * 8);
;           bf16x8 b0 = lds_b128(sB + (jt0 * 16 + frc) * S_LDB + ks * 32 + fqc * 8);
;           bf16x8 b1 = lds_b128(sB + ((jt0 + 1) * 16 + frc) * S_LDB + ks * 32 + fqc * 8);
;           cb[0] = mfma16(a, b0, cb[0]);
;           cb[1] = mfma16(a, b1, cb[1]);
;         }
;         const int i0 = it * 16 + fqc * 4;
; #pragma unroll
;         for (int hh = 0; hh < 2; ++hh) {
;           const float* hAc = sAc + hh * 256;
;           const float* hDt = sDt + hh * 256;
;           const f32x4 aci = *(const f32x4*)(hAc + i0);
; #pragma unroll
;           for (int t = 0; t < 2; ++t) {
;             const int jj = (jt0 + t) * 16 + frc;
;             const float acj = hAc[jj], dtj = hDt[jj];
; #pragma unroll
;             for (int j = 0; j < 4; ++j) {
;               const float gv = (jj <= i0 + j) ? cb[t][j] * __expf(aci[j] - acj) * dtj : 0.f;
;               sG[(hh * 64 + i0 + j) * S_LDT + jj] = f2bf(gv);
;             }
;           }
;         }
;       }
.LBB0_429:
	v_mov_b32_e32 v92, v112
	v_mov_b32_e32 v95, v141
	s_mov_b32 s50, 0
	v_add_u32_e32 v0, s56, v92
	v_mul_lo_u32 v80, v0, s63
	v_lshlrev_b32_e32 v0, 4, v95
	v_add_u32_e32 v97, s53, v92
	v_add3_u32 v93, s64, v80, v0
	v_mul_lo_u32 v80, v97, s63
	v_add_u32_e32 v99, s72, v92
	v_add3_u32 v96, s64, v80, v0
	v_mul_lo_u32 v80, v99, s63
	v_add3_u32 v98, s64, v80, v0
	ds_read_b128 v[80:83], v93 offset:17408
	ds_read_b128 v[84:87], v96
	ds_read_b128 v[88:91], v98
	s_waitcnt lgkmcnt(1)
	v_mfma_f32_16x16x32_bf16 v[84:87], v[80:83], v[84:87], 0
	v_lshlrev_b32_e32 v94, 3, v95
	s_waitcnt lgkmcnt(0)
	v_mfma_f32_16x16x32_bf16 v[80:83], v[80:83], v[88:91], 0
	ds_read_b128 v[88:91], v93 offset:17472
	ds_read_b128 v[100:103], v96 offset:64
	ds_read_b128 v[104:107], v98 offset:64
	s_waitcnt lgkmcnt(1)
	v_mfma_f32_16x16x32_bf16 v[84:87], v[88:91], v[100:103], v[84:87]
	s_waitcnt lgkmcnt(0)
	v_mfma_f32_16x16x32_bf16 v[80:83], v[88:91], v[104:107], v[80:83]
	ds_read_b128 v[88:91], v93 offset:17536
	ds_read_b128 v[100:103], v96 offset:128
	ds_read_b128 v[104:107], v98 offset:128
	s_waitcnt lgkmcnt(1)
	v_mfma_f32_16x16x32_bf16 v[84:87], v[88:91], v[100:103], v[84:87]
	s_waitcnt lgkmcnt(0)
	v_mfma_f32_16x16x32_bf16 v[80:83], v[88:91], v[104:107], v[80:83]
	ds_read_b128 v[100:103], v93 offset:17600
	ds_read_b128 v[88:91], v96 offset:192
	ds_read_b128 v[104:107], v98 offset:192
	v_lshlrev_b32_e32 v96, 2, v95
	v_lshlrev_b32_e32 v98, 2, v97
	s_waitcnt lgkmcnt(1)
	v_mfma_f32_16x16x32_bf16 v[88:91], v[100:103], v[88:91], v[84:87]
	v_add_u32_e32 v93, s84, v98
	s_waitcnt lgkmcnt(0)
	v_mfma_f32_16x16x32_bf16 v[80:83], v[100:103], v[104:107], v[80:83]
	v_add_u32_e32 v100, s56, v96
	v_lshlrev_b32_e32 v101, 2, v100
	v_add_u32_e32 v84, s84, v101
	ds_read_b128 v[84:87], v84
	ds_read_b32 v102, v93
	v_add_u32_e32 v93, s62, v98
	ds_read_b32 v103, v93
	v_cmp_gt_i32_e64 s[40:41], v97, v100
	v_lshlrev_b32_e32 v105, 1, v97
	s_waitcnt lgkmcnt(1)
	v_sub_f32_e32 v93, v84, v102
	v_mul_f32_e32 v93, 0x3fb8aa3b, v93
	v_exp_f32_e32 v93, v93
	v_cmp_gt_i32_e32 vcc, v99, v100
	v_add_u32_e32 v96, s67, v96
	v_mul_f32_e32 v93, v88, v93
	s_waitcnt lgkmcnt(0)
	v_mul_f32_e32 v93, v103, v93
	v_cndmask_b32_e64 v93, v93, 0, s[40:41]
	v_bfe_u32 v104, v93, 16, 1
	v_add3_u32 v104, v93, v104, s96
	v_mul_lo_u32 v93, v100, s87
	v_add3_u32 v93, s95, v93, v105
	v_sub_f32_e32 v105, v85, v102
	v_mul_f32_e32 v105, 0x3fb8aa3b, v105
	v_exp_f32_e32 v105, v105
	ds_write_b16_d16_hi v93, v104
	v_or_b32_e32 v104, 1, v100
	v_cmp_gt_i32_e64 s[42:43], v97, v104
	v_mul_f32_e32 v105, v89, v105
	v_mul_f32_e32 v105, v103, v105
	v_cndmask_b32_e64 v105, v105, 0, s[42:43]
	v_bfe_u32 v106, v105, 16, 1
	v_add3_u32 v105, v105, v106, s96
	v_sub_f32_e32 v106, v86, v102
	v_mul_f32_e32 v106, 0x3fb8aa3b, v106
	v_exp_f32_e32 v106, v106
	ds_write_b16_d16_hi v93, v105 offset:144
	v_or_b32_e32 v105, 2, v100
	v_cmp_gt_i32_e64 s[44:45], v97, v105
	v_mul_f32_e32 v106, v90, v106
	v_mul_f32_e32 v106, v103, v106
	v_cndmask_b32_e64 v106, v106, 0, s[44:45]
	v_bfe_u32 v107, v106, 16, 1
	v_add3_u32 v106, v106, v107, s96
	ds_write_b16_d16_hi v93, v106 offset:288
	v_or_b32_e32 v106, 3, v100
	v_cmp_gt_i32_e64 s[46:47], v97, v106
	v_sub_f32_e32 v97, v87, v102
	v_mul_f32_e32 v97, 0x3fb8aa3b, v97
	v_exp_f32_e32 v97, v97
	v_cmp_gt_i32_e64 s[38:39], v99, v104
	v_cmp_gt_i32_e64 s[36:37], v99, v105
	v_cmp_gt_i32_e64 s[34:35], v99, v106
	v_mul_f32_e32 v97, v91, v97
	v_mul_f32_e32 v97, v103, v97
	v_cndmask_b32_e64 v97, v97, 0, s[46:47]
	v_bfe_u32 v102, v97, 16, 1
	v_add3_u32 v97, v97, v102, s96
	ds_write_b16_d16_hi v93, v97 offset:432
	v_lshlrev_b32_e32 v97, 2, v99
	v_add_u32_e32 v102, s84, v97
	ds_read_b32 v102, v102
	v_add_u32_e32 v99, s2, v98
	ds_read_b32 v99, v99
	v_add_u32_e32 v103, s62, v97
	ds_read_b32 v103, v103
	s_waitcnt lgkmcnt(2)
	v_sub_f32_e32 v84, v84, v102
	v_mul_f32_e32 v84, 0x3fb8aa3b, v84
	v_exp_f32_e32 v84, v84
	v_add_u32_e32 v98, s52, v98
	ds_read_b32 v98, v98
	v_mul_f32_e32 v84, v80, v84
	s_waitcnt lgkmcnt(1)
; __device__ __forceinline__ void phase_ssd(KP P, char* smem, const int wv) {
;     ...
;         for (int hh = 0; hh < 2; ++hh) {
;           const float* hAc = sAc + hh * 256;
;           const float* hDt = sDt + hh * 256;
;           const f32x4 aci = *(const f32x4*)(hAc + i0);
; #pragma unroll
;           for (int t = 0; t < 2; ++t) {
;             const int jj = (jt0 + t) * 16 + frc;
;             const float acj = hAc[jj], dtj = hDt[jj];
; #pragma unroll
;             for (int j = 0; j < 4; ++j) {
;               const float gv = (jj <= i0 + j) ? cb[t][j] * __expf(aci[j] - acj) * dtj : 0.f;
;               sG[(hh * 64 + i0 + j) * S_LDT + jj] = f2bf(gv);
;             }
;           }
;         }
;       }
;       lds_barrier();
;       const bfu* xrow = sXT + (hl * 64 + ps * 16 + frc) * S_LDT;
; #pragma unroll 1
;       for (int it = 0; it < 4; ++it) {
;         f32x4 yacc = {0.f, 0.f, 0.f, 0.f}, oacc = {0.f, 0.f, 0.f, 0.f};
;         const bfu* grow = sG + (hl * 64 + it * 16 + frc) * S_LDT;
	v_mul_f32_e32 v84, v103, v84
	v_cndmask_b32_e64 v84, v84, 0, vcc
	v_bfe_u32 v100, v84, 16, 1
	v_add3_u32 v84, v84, v100, s96
	ds_write_b16_d16_hi v93, v84 offset:32
	v_sub_f32_e32 v84, v85, v102
	v_mul_f32_e32 v84, 0x3fb8aa3b, v84
	v_exp_f32_e32 v84, v84
	s_nop 0
	v_mul_f32_e32 v84, v81, v84
	v_mul_f32_e32 v84, v103, v84
	v_cndmask_b32_e64 v84, v84, 0, s[38:39]
	v_bfe_u32 v85, v84, 16, 1
	v_add3_u32 v84, v84, v85, s96
	ds_write_b16_d16_hi v93, v84 offset:176
	v_sub_f32_e32 v84, v86, v102
	v_mul_f32_e32 v84, 0x3fb8aa3b, v84
	v_exp_f32_e32 v84, v84
	s_nop 0
	v_mul_f32_e32 v84, v82, v84
	v_mul_f32_e32 v84, v103, v84
	v_cndmask_b32_e64 v84, v84, 0, s[36:37]
	v_bfe_u32 v85, v84, 16, 1
	v_add3_u32 v84, v84, v85, s96
	ds_write_b16_d16_hi v93, v84 offset:320
	v_sub_f32_e32 v84, v87, v102
	v_mul_f32_e32 v84, 0x3fb8aa3b, v84
	v_exp_f32_e32 v84, v84
	v_add_u32_e32 v102, s59, v0
	v_mul_f32_e32 v84, v83, v84
	v_mul_f32_e32 v84, v103, v84
	v_cndmask_b32_e64 v84, v84, 0, s[34:35]
	v_bfe_u32 v85, v84, 16, 1
	v_add3_u32 v84, v84, v85, s96
	ds_write_b16_d16_hi v93, v84 offset:464
	v_add_u32_e32 v84, s2, v101
	ds_read_b128 v[84:87], v84
	s_waitcnt lgkmcnt(0)
	v_sub_f32_e32 v100, v84, v99
	v_mul_f32_e32 v100, 0x3fb8aa3b, v100
	v_exp_f32_e32 v100, v100
	s_nop 0
	v_mul_f32_e32 v88, v88, v100
	v_mul_f32_e32 v88, v98, v88
	v_cndmask_b32_e64 v88, v88, 0, s[40:41]
	v_bfe_u32 v100, v88, 16, 1
	v_add3_u32 v88, v88, v100, s96
	ds_write_b16_d16_hi v93, v88 offset:9216
	v_sub_f32_e32 v88, v85, v99
	v_mul_f32_e32 v88, 0x3fb8aa3b, v88
	v_exp_f32_e32 v88, v88
	s_nop 0
	v_mul_f32_e32 v88, v89, v88
	v_mul_f32_e32 v88, v98, v88
	v_cndmask_b32_e64 v88, v88, 0, s[42:43]
	v_bfe_u32 v89, v88, 16, 1
	v_add3_u32 v88, v88, v89, s96
	ds_write_b16_d16_hi v93, v88 offset:9360
	v_sub_f32_e32 v88, v86, v99
	v_mul_f32_e32 v88, 0x3fb8aa3b, v88
	v_exp_f32_e32 v88, v88
	s_nop 0
	v_mul_f32_e32 v88, v90, v88
	v_mul_f32_e32 v88, v98, v88
	v_cndmask_b32_e64 v88, v88, 0, s[44:45]
	v_bfe_u32 v89, v88, 16, 1
	v_add3_u32 v88, v88, v89, s96
	ds_write_b16_d16_hi v93, v88 offset:9504
	v_sub_f32_e32 v88, v87, v99
	v_mul_f32_e32 v88, 0x3fb8aa3b, v88
	v_exp_f32_e32 v88, v88
	s_nop 0
	v_mul_f32_e32 v88, v91, v88
	v_mul_f32_e32 v88, v98, v88
	v_cndmask_b32_e64 v88, v88, 0, s[46:47]
	v_bfe_u32 v89, v88, 16, 1
	v_add3_u32 v88, v88, v89, s96
	ds_write_b16_d16_hi v93, v88 offset:9648
	v_add_u32_e32 v88, s2, v97
	ds_read_b32 v88, v88
	v_add_u32_e32 v89, s52, v97
	ds_read_b32 v89, v89
	v_mul_lo_u32 v97, v92, s87
	v_add3_u32 v99, v97, v0, s58
	s_waitcnt lgkmcnt(1)
	v_sub_f32_e32 v84, v84, v88
	v_mul_f32_e32 v84, 0x3fb8aa3b, v84
	v_exp_f32_e32 v84, v84
	s_nop 0
	v_mul_f32_e32 v80, v80, v84
	s_waitcnt lgkmcnt(0)
	v_mul_f32_e32 v80, v89, v80
	v_cndmask_b32_e64 v80, v80, 0, vcc
	v_bfe_u32 v84, v80, 16, 1
	v_add3_u32 v80, v80, v84, s96
	ds_write_b16_d16_hi v93, v80 offset:9248
	v_sub_f32_e32 v80, v85, v88
	v_mul_f32_e32 v80, 0x3fb8aa3b, v80
	v_exp_f32_e32 v80, v80
	v_cmp_eq_u32_e32 vcc, 0, v92
	v_mul_f32_e32 v80, v81, v80
	v_mul_f32_e32 v80, v89, v80
	v_cndmask_b32_e64 v80, v80, 0, s[38:39]
	v_bfe_u32 v81, v80, 16, 1
	v_add3_u32 v80, v80, v81, s96
	ds_write_b16_d16_hi v93, v80 offset:9392
	v_sub_f32_e32 v80, v86, v88
	v_mul_f32_e32 v80, 0x3fb8aa3b, v80
	v_exp_f32_e32 v80, v80
	s_nop 0
	v_mul_f32_e32 v80, v82, v80
	v_mul_f32_e32 v80, v89, v80
	v_cndmask_b32_e64 v80, v80, 0, s[36:37]
	v_bfe_u32 v81, v80, 16, 1
	v_add3_u32 v80, v80, v81, s96
	ds_write_b16_d16_hi v93, v80 offset:9536
	v_sub_f32_e32 v80, v87, v88
	v_mul_f32_e32 v80, 0x3fb8aa3b, v80
	v_exp_f32_e32 v80, v80
	v_add_u32_e32 v82, s73, v92
	s_mov_b32 s36, 0
	v_mul_f32_e32 v80, v83, v80
	v_mul_f32_e32 v80, v89, v80
	v_cndmask_b32_e64 v80, v80, 0, s[34:35]
	v_bfe_u32 v81, v80, 16, 1
	v_add3_u32 v80, v80, v81, s96
	ds_write_b16_d16_hi v93, v80 offset:9680
	v_mad_u64_u32 v[80:81], s[34:35], v92, s63, v[0:1]
	s_waitcnt lgkmcnt(0)
	s_barrier
	v_readlane_b32 s34, v241, 28
	s_nop 3
	s_cmp_lt_u32 s34, 4
	s_cbranch_scc1 .Lssd_prio_skip
	s_setprio 1
.Lssd_prio_skip:
	v_mul_lo_u32 v83, v82, s87
	v_ashrrev_i32_e32 v93, 31, v92
	s_add_i32 s34, 0, 0x4400
	v_add_u32_e32 v98, s9, v80
	v_lshl_add_u64 v[88:89], v[92:93], 1, s[4:5]
	v_add3_u32 v93, s64, v83, v0
	v_add_u32_e32 v100, s34, v80
	s_add_i32 s34, 0, 0xd000
	v_mul_lo_u32 v0, v95, s57
	v_lshlrev_b32_e32 v80, 1, v82
	v_add3_u32 v101, v83, v94, s34
	v_add3_u32 v95, v0, v80, 0
	ds_read_b128 v[212:215], v98
	ds_read_b128 v[216:219], v98 offset:64
	ds_read_b128 v[220:223], v98 offset:128
	ds_read_b128 v[224:227], v98 offset:192
	ds_read_b128 v[228:231], v93 offset:53248
	ds_read_b128 v[232:235], v93 offset:53312

; __device__ __forceinline__ void phase_ssd(KP P, char* smem, const int wv) {
;     ...
;       {
;         const float dec = __expf(a63);
; #pragma unroll
;         for (int nt = 0; nt < 8; ++nt) hacc[nt] *= dec;
; #pragma unroll
;         for (int ks = 0; ks < 2; ++ks) {
;           const int j0 = ks * 32 + fqc * 8;
;           bf16x8 xr = lds_b128(xrow + j0);
;           f32x4 w0 = *(const f32x4*)(myW + j0), w1 = *(const f32x4*)(myW + j0 + 4);
;           u32x4 xu = __builtin_bit_cast(u32x4, xr);
;           u32x4 pk;
;           pk[0] = cvt_pk_bf16(__uint_as_float(xu[0] << 16) * w0[0], __uint_as_float(xu[0] & 0xffff0000u) * w0[1]);
;           pk[1] = cvt_pk_bf16(__uint_as_float(xu[1] << 16) * w0[2], __uint_as_float(xu[1] & 0xffff0000u) * w0[3]);
;           pk[2] = cvt_pk_bf16(__uint_as_float(xu[2] << 16) * w1[0], __uint_as_float(xu[2] & 0xffff0000u) * w1[1]);
;           pk[3] = cvt_pk_bf16(__uint_as_float(xu[3] << 16) * w1[2], __uint_as_float(xu[3] & 0xffff0000u) * w1[3]);
;           bf16x8 af = __builtin_bit_cast(bf16x8, pk);
; #pragma unroll
;           for (int nt = 0; nt < 8; ++nt) {
;             bf16x8 b = lds_b128(sBT + (nt * 16 + frc) * S_LDT + j0);
;             hacc[nt] = mfma16(af, b, hacc[nt]);
;           }
;         }
.LBB0_441:
	v_mul_f32_e32 v80, s49, v175
	v_exp_f32_e32 v80, v80
	v_lshlrev_b32_e32 v95, 1, v94
	v_lshl_add_u32 v94, v94, 2, s70
	v_add3_u32 v95, s64, v95, v97
	v_pk_mul_f32 v[30:31], v[30:31], v[80:81] op_sel_hi:[1,0]
	v_pk_mul_f32 v[28:29], v[28:29], v[80:81] op_sel_hi:[1,0]
	v_pk_mul_f32 v[34:35], v[34:35], v[80:81] op_sel_hi:[1,0]
	v_pk_mul_f32 v[32:33], v[32:33], v[80:81] op_sel_hi:[1,0]
	v_pk_mul_f32 v[22:23], v[22:23], v[80:81] op_sel_hi:[1,0]
	v_pk_mul_f32 v[20:21], v[20:21], v[80:81] op_sel_hi:[1,0]
	v_pk_mul_f32 v[26:27], v[26:27], v[80:81] op_sel_hi:[1,0]
	v_pk_mul_f32 v[24:25], v[24:25], v[80:81] op_sel_hi:[1,0]
	v_pk_mul_f32 v[14:15], v[14:15], v[80:81] op_sel_hi:[1,0]
	v_pk_mul_f32 v[12:13], v[12:13], v[80:81] op_sel_hi:[1,0]
	v_pk_mul_f32 v[18:19], v[18:19], v[80:81] op_sel_hi:[1,0]
	v_pk_mul_f32 v[16:17], v[16:17], v[80:81] op_sel_hi:[1,0]
	v_pk_mul_f32 v[6:7], v[6:7], v[80:81] op_sel_hi:[1,0]
	v_pk_mul_f32 v[4:5], v[4:5], v[80:81] op_sel_hi:[1,0]
	v_pk_mul_f32 v[10:11], v[10:11], v[80:81] op_sel_hi:[1,0]
	v_pk_mul_f32 v[8:9], v[8:9], v[80:81] op_sel_hi:[1,0]
	ds_read_b128 v[84:87], v94
	ds_read_b128 v[88:91], v94 offset:16
	ds_read_b128 v[104:107], v94 offset:128
	ds_read_b128 v[108:111], v94 offset:144
	ds_read_b128 v[156:159], v95 offset:34816
	ds_read_b128 v[160:163], v95 offset:37120
	ds_read_b128 v[208:211], v95 offset:39424
	ds_read_b128 v[212:215], v95 offset:41728
	ds_read_b128 v[216:219], v95 offset:44032
	ds_read_b128 v[220:223], v95 offset:46336
	ds_read_b128 v[224:227], v95 offset:48640
	ds_read_b128 v[236:239], v95 offset:50944
	s_waitcnt lgkmcnt(8)
	v_lshlrev_b32_e32 v96, 16, v228
	v_and_b32_e32 v97, 0xffff0000, v228
	v_mul_f32_e32 v96, v84, v96
	v_mul_f32_e32 v97, v85, v97
	v_cvt_pk_bf16_f32 v80, v96, v97
	v_lshlrev_b32_e32 v96, 16, v229
	v_and_b32_e32 v97, 0xffff0000, v229
	v_mul_f32_e32 v96, v86, v96
	v_mul_f32_e32 v97, v87, v97
	v_cvt_pk_bf16_f32 v81, v96, v97
	v_lshlrev_b32_e32 v96, 16, v230
	v_and_b32_e32 v97, 0xffff0000, v230
	v_mul_f32_e32 v96, v88, v96
	v_mul_f32_e32 v97, v89, v97
	v_cvt_pk_bf16_f32 v82, v96, v97
	v_lshlrev_b32_e32 v96, 16, v231
	v_and_b32_e32 v97, 0xffff0000, v231
	v_mul_f32_e32 v96, v90, v96
	v_mul_f32_e32 v97, v91, v97
	v_cvt_pk_bf16_f32 v83, v96, v97
	v_lshlrev_b32_e32 v96, 16, v232
	v_and_b32_e32 v97, 0xffff0000, v232
	v_mul_f32_e32 v96, v104, v96
	v_mul_f32_e32 v97, v105, v97
	v_cvt_pk_bf16_f32 v100, v96, v97
	v_lshlrev_b32_e32 v96, 16, v233
	v_and_b32_e32 v97, 0xffff0000, v233
	v_mul_f32_e32 v96, v106, v96
	v_mul_f32_e32 v97, v107, v97
	v_cvt_pk_bf16_f32 v101, v96, v97
	v_lshlrev_b32_e32 v96, 16, v234
	v_and_b32_e32 v97, 0xffff0000, v234
	v_mul_f32_e32 v96, v108, v96
	v_mul_f32_e32 v97, v109, v97
	v_cvt_pk_bf16_f32 v102, v96, v97
	v_lshlrev_b32_e32 v96, 16, v235
	v_and_b32_e32 v97, 0xffff0000, v235
	v_mul_f32_e32 v96, v110, v96
	v_mul_f32_e32 v97, v111, v97
	v_cvt_pk_bf16_f32 v103, v96, v97
	s_waitcnt lgkmcnt(7)
	v_mfma_f32_16x16x32_bf16 v[28:31], v[80:83], v[156:159], v[28:31]
	ds_read_b128 v[156:159], v95 offset:34880
	s_waitcnt lgkmcnt(7)
	v_mfma_f32_16x16x32_bf16 v[32:35], v[80:83], v[160:163], v[32:35]
	ds_read_b128 v[160:163], v95 offset:37184
	s_waitcnt lgkmcnt(7)
	v_mfma_f32_16x16x32_bf16 v[20:23], v[80:83], v[208:211], v[20:23]
	ds_read_b128 v[208:211], v95 offset:39488
	s_waitcnt lgkmcnt(7)
	v_mfma_f32_16x16x32_bf16 v[24:27], v[80:83], v[212:215], v[24:27]
	ds_read_b128 v[212:215], v95 offset:41792
	s_waitcnt lgkmcnt(7)
	v_mfma_f32_16x16x32_bf16 v[12:15], v[80:83], v[216:219], v[12:15]
	ds_read_b128 v[216:219], v95 offset:44096
	s_waitcnt lgkmcnt(7)
	v_mfma_f32_16x16x32_bf16 v[16:19], v[80:83], v[220:223], v[16:19]
	ds_read_b128 v[220:223], v95 offset:46400
	s_waitcnt lgkmcnt(7)
	v_mfma_f32_16x16x32_bf16 v[4:7], v[80:83], v[224:227], v[4:7]
	ds_read_b128 v[224:227], v95 offset:48704
	s_waitcnt lgkmcnt(7)
	v_mfma_f32_16x16x32_bf16 v[8:11], v[80:83], v[236:239], v[8:11]
	ds_read_b128 v[236:239], v95 offset:51008
	s_waitcnt lgkmcnt(7)
	v_mfma_f32_16x16x32_bf16 v[28:31], v[100:103], v[156:159], v[28:31]
	s_waitcnt lgkmcnt(6)
	v_mfma_f32_16x16x32_bf16 v[32:35], v[100:103], v[160:163], v[32:35]
	s_waitcnt lgkmcnt(5)
	v_mfma_f32_16x16x32_bf16 v[20:23], v[100:103], v[208:211], v[20:23]
	s_waitcnt lgkmcnt(4)
	v_mfma_f32_16x16x32_bf16 v[24:27], v[100:103], v[212:215], v[24:27]
	s_waitcnt lgkmcnt(3)
; __device__ __forceinline__ void phase_ssd(KP P, char* smem, const int wv) {
;     ...
;           for (int nt = 0; nt < 8; ++nt) {
;             bf16x8 b = lds_b128(sBT + (nt * 16 + frc) * S_LDT + j0);
;             hacc[nt] = mfma16(af, b, hacc[nt]);
;           }
;         }
; #pragma unroll
;         for (int nt = 0; nt < 8; ++nt)
; #pragma unroll
;           for (int j = 0; j < 4; ++j) myH[(fqc * 4 + j) * S_LDB + nt * 16 + frc] = f2bf(hacc[nt][j]);
;       }
;       lds_barrier();
;       if (tid < 64) {
;         float sm = 0.f;
; #pragma unroll
;         for (int ww = 0; ww < 8; ++ww) sm += sSq[ww * 64 + tid];
;         ssqp[(size_t)(r0 + tid) * 16 + g * 4 + hp] = sm;
;       }
	v_mfma_f32_16x16x32_bf16 v[12:15], v[100:103], v[216:219], v[12:15]
	s_waitcnt lgkmcnt(2)
	v_mfma_f32_16x16x32_bf16 v[16:19], v[100:103], v[220:223], v[16:19]
	s_waitcnt lgkmcnt(1)
	v_mfma_f32_16x16x32_bf16 v[4:7], v[100:103], v[224:227], v[4:7]
	s_waitcnt lgkmcnt(0)
	v_mfma_f32_16x16x32_bf16 v[8:11], v[100:103], v[236:239], v[8:11]
	v_bfe_u32 v80, v28, 16, 1
	v_lshlrev_b32_e32 v81, 1, v92
	v_add3_u32 v80, v28, v80, s96
	v_add3_u32 v0, s9, v81, v0
	ds_write_b16_d16_hi v0, v80
	v_bfe_u32 v80, v29, 16, 1
	v_add3_u32 v80, v29, v80, s96
	ds_write_b16_d16_hi v0, v80 offset:272
	v_bfe_u32 v80, v30, 16, 1
	v_add3_u32 v80, v30, v80, s96
	ds_write_b16_d16_hi v0, v80 offset:544
	v_bfe_u32 v80, v31, 16, 1
	v_add3_u32 v80, v31, v80, s96
	ds_write_b16_d16_hi v0, v80 offset:816
	v_bfe_u32 v80, v32, 16, 1
	v_add3_u32 v80, v32, v80, s96
	ds_write_b16_d16_hi v0, v80 offset:32
	v_bfe_u32 v80, v33, 16, 1
	v_add3_u32 v80, v33, v80, s96
	ds_write_b16_d16_hi v0, v80 offset:304
	v_bfe_u32 v80, v34, 16, 1
	v_add3_u32 v80, v34, v80, s96
	ds_write_b16_d16_hi v0, v80 offset:576
	v_bfe_u32 v80, v35, 16, 1
	v_add3_u32 v80, v35, v80, s96
	ds_write_b16_d16_hi v0, v80 offset:848
	v_bfe_u32 v80, v20, 16, 1
	v_add3_u32 v80, v20, v80, s96
	ds_write_b16_d16_hi v0, v80 offset:64
	v_bfe_u32 v80, v21, 16, 1
	v_add3_u32 v80, v21, v80, s96
	ds_write_b16_d16_hi v0, v80 offset:336
	v_bfe_u32 v80, v22, 16, 1
	v_add3_u32 v80, v22, v80, s96
	ds_write_b16_d16_hi v0, v80 offset:608
	v_bfe_u32 v80, v23, 16, 1
	v_add3_u32 v80, v23, v80, s96
	ds_write_b16_d16_hi v0, v80 offset:880
	v_bfe_u32 v80, v24, 16, 1
	v_add3_u32 v80, v24, v80, s96
	ds_write_b16_d16_hi v0, v80 offset:96
	v_bfe_u32 v80, v25, 16, 1
	v_add3_u32 v80, v25, v80, s96
	ds_write_b16_d16_hi v0, v80 offset:368
	v_bfe_u32 v80, v26, 16, 1
	v_add3_u32 v80, v26, v80, s96
	ds_write_b16_d16_hi v0, v80 offset:640
	v_bfe_u32 v80, v27, 16, 1
	v_add3_u32 v80, v27, v80, s96
	ds_write_b16_d16_hi v0, v80 offset:912
	v_bfe_u32 v80, v12, 16, 1
	v_add3_u32 v80, v12, v80, s96
	ds_write_b16_d16_hi v0, v80 offset:128
	v_bfe_u32 v80, v13, 16, 1
	v_add3_u32 v80, v13, v80, s96
	ds_write_b16_d16_hi v0, v80 offset:400
	v_bfe_u32 v80, v14, 16, 1
	v_add3_u32 v80, v14, v80, s96
	ds_write_b16_d16_hi v0, v80 offset:672
	v_bfe_u32 v80, v15, 16, 1
	v_add3_u32 v80, v15, v80, s96
	ds_write_b16_d16_hi v0, v80 offset:944
	v_bfe_u32 v80, v16, 16, 1
	v_add3_u32 v80, v16, v80, s96
	ds_write_b16_d16_hi v0, v80 offset:160
	v_bfe_u32 v80, v17, 16, 1
	v_add3_u32 v80, v17, v80, s96
	ds_write_b16_d16_hi v0, v80 offset:432
	v_bfe_u32 v80, v18, 16, 1
	v_add3_u32 v80, v18, v80, s96
	ds_write_b16_d16_hi v0, v80 offset:704
	v_bfe_u32 v80, v19, 16, 1
	v_add3_u32 v80, v19, v80, s96
	ds_write_b16_d16_hi v0, v80 offset:976
	v_bfe_u32 v80, v4, 16, 1
	v_add3_u32 v80, v4, v80, s96
	ds_write_b16_d16_hi v0, v80 offset:192
	v_bfe_u32 v80, v5, 16, 1
	v_add3_u32 v80, v5, v80, s96
	ds_write_b16_d16_hi v0, v80 offset:464
	v_bfe_u32 v80, v6, 16, 1
	v_add3_u32 v80, v6, v80, s96
	ds_write_b16_d16_hi v0, v80 offset:736
	v_bfe_u32 v80, v7, 16, 1
	v_add3_u32 v80, v7, v80, s96
	ds_write_b16_d16_hi v0, v80 offset:1008
	v_bfe_u32 v80, v8, 16, 1
	v_add3_u32 v80, v8, v80, s96
	ds_write_b16_d16_hi v0, v80 offset:224
	v_bfe_u32 v80, v9, 16, 1
	v_add3_u32 v80, v9, v80, s96
	ds_write_b16_d16_hi v0, v80 offset:496
	v_bfe_u32 v80, v10, 16, 1
	v_add3_u32 v80, v10, v80, s96
	ds_write_b16_d16_hi v0, v80 offset:768
	v_bfe_u32 v80, v11, 16, 1
	v_add3_u32 v80, v11, v80, s96
	ds_write_b16_d16_hi v0, v80 offset:1040
	s_waitcnt lgkmcnt(0)
	s_barrier
	s_setprio 0
	s_and_saveexec_b64 s[34:35], s[14:15]
	s_cbranch_execz .LBB0_414
	ds_read2st64_b32 v[80:81], v204 offset1:1
	ds_read2st64_b32 v[82:83], v204 offset0:2 offset1:3
	ds_read2st64_b32 v[84:85], v204 offset0:4 offset1:5
	ds_read2st64_b32 v[86:87], v204 offset0:6 offset1:7
	v_add_u32_e32 v88, s48, v113
	v_ashrrev_i32_e32 v89, 31, v88
	v_lshlrev_b64 v[88:89], 6, v[88:89]
	v_lshl_add_u64 v[88:89], s[80:81], 0, v[88:89]
	s_waitcnt lgkmcnt(0)
	v_add_f32_e32 v0, 0, v80
	v_add_f32_e32 v0, v0, v81
	v_add_f32_e32 v0, v0, v82
	v_add_f32_e32 v0, v0, v83
	v_add_f32_e32 v0, v0, v84
	v_add_f32_e32 v0, v0, v85
	v_add_f32_e32 v0, v0, v86
	v_add_f32_e32 v0, v0, v87
	global_store_dword v[88:89], v0, off
	s_branch .LBB0_414
